# decode-row norm tail (P2,P10): pre-norm gain vectors preloaded, no per-store reload waits
# baseline (speedup 1.0000x reference)
; __device__ __forceinline__ float bflo(unsigned w) { return __uint_as_float(w << 16); }
; __device__ __forceinline__ float bfhi(unsigned w) { return __uint_as_float(w & 0xffff0000u); }
; template <int NEXT, int SRC> __device__ __forceinline__ void norm_rows(const Args& a, const bf16* Fin, float coef, int i_post, int i_pre, int first, int NGW, int end, int lane) {
;     ...
;     for (int m0 = first; m0 < end; m0 += 2 * NGW) {
;         f32x4 f[2][4], x[2][4]; float s[2] = {0.f, 0.f};
; #pragma unroll
;         for (int q = 0; q < 2; ++q) { const int m = m0 + q * NGW; const bool ok = m < end; const int mm = ok ? m : m0;
;             const float* xr = SRC == 0 ? xrow_ptr(a, mm, z) : nullptr;
;             const bf16* xb = (SRC == 1 ? XR : XN) + (size_t)mm * DM;
; #pragma unroll
;             for (int j = 0; j < 4; ++j) {
;                 const u32x2 w = ((const u32x2*)(Fin + (size_t)mm * DM))[lane + 64 * j];
;                 f[q][j] = (f32x4){bflo(w.x), bfhi(w.x), bflo(w.y), bfhi(w.y)};
;                 if constexpr (SRC == 0) x[q][j] = ((const f32x4*)xr)[lane + 64 * j];
;                 else { const u32x2 xw = ((const u32x2*)xb)[lane + 64 * j]; x[q][j] = (f32x4){bflo(xw.x), bfhi(xw.x), bflo(xw.y), bfhi(xw.y)}; }
;                 s[q] += (f[q][j].x * f[q][j].x + f[q][j].y * f[q][j].y) + (f[q][j].z * f[q][j].z + f[q][j].w * f[q][j].w);
;             } }
.LBB0_387:
	s_lshl_b64 s[22:23], s[20:21], 11
	v_lshl_add_u64 v[8:9], v[34:35], 0, s[22:23]
	global_load_dwordx4 v[100:103], v[38:39], off
	global_load_dwordx4 v[104:107], v[38:39], off offset:1024
	global_load_dwordx4 v[108:111], v[38:39], off offset:2048
	global_load_dwordx4 v[112:115], v[38:39], off offset:3072
	global_load_dwordx4 v[24:27], v32, s[6:7]
	global_load_dwordx4 v[20:23], v32, s[6:7] offset:1024
	global_load_dwordx2 v[6:7], v[8:9], off
	global_load_dwordx2 v[4:5], v[8:9], off offset:512
	global_load_dwordx2 v[2:3], v[8:9], off offset:1024
	global_load_dwordx2 v[0:1], v[8:9], off offset:1536
	global_load_dwordx4 v[28:31], v32, s[6:7] offset:2048
	global_load_dwordx4 v[16:19], v32, s[6:7] offset:3072
	s_add_i32 s19, s18, 8
	s_cmp_lt_i32 s19, s34
	s_cselect_b64 s[20:21], -1, 0
	s_and_b64 s[6:7], s[20:21], exec
	s_cselect_b32 s6, s19, s18
	s_cmpk_lt_i32 s6, 0x4000
	s_mov_b64 s[26:27], -1
	s_cbranch_scc1 .LBB0_389
	s_load_dwordx2 s[24:25], s[12:13], 0x8
	s_add_i32 s26, s6, 0xffffc000
	s_mov_b32 s27, s1
	s_lshl_b64 s[26:27], s[26:27], 12
	s_mov_b32 s7, s1
	s_waitcnt lgkmcnt(0)
	s_add_u32 s24, s24, s26
	s_addc_u32 s25, s25, s27
	s_mov_b64 s[26:27], 0

; __device__ __forceinline__ float bflo(unsigned w) { return __uint_as_float(w << 16); }
; __device__ __forceinline__ float bfhi(unsigned w) { return __uint_as_float(w & 0xffff0000u); }
; template <int NEXT, int SRC> __device__ __forceinline__ void norm_rows(const Args& a, const bf16* Fin, float coef, int i_post, int i_pre, int first, int NGW, int end, int lane) {
;     ...
;         for (int q = 0; q < 2; ++q) { const int m = m0 + q * NGW; const bool ok = m < end; const int mm = ok ? m : m0;
;             const float* xr = SRC == 0 ? xrow_ptr(a, mm, z) : nullptr;
;             const bf16* xb = (SRC == 1 ? XR : XN) + (size_t)mm * DM;
; #pragma unroll
;             for (int j = 0; j < 4; ++j) {
;                 const u32x2 w = ((const u32x2*)(Fin + (size_t)mm * DM))[lane + 64 * j];
;                 f[q][j] = (f32x4){bflo(w.x), bfhi(w.x), bflo(w.y), bfhi(w.y)};
;                 if constexpr (SRC == 0) x[q][j] = ((const f32x4*)xr)[lane + 64 * j];
;                 else { const u32x2 xw = ((const u32x2*)xb)[lane + 64 * j]; x[q][j] = (f32x4){bflo(xw.x), bfhi(xw.x), bflo(xw.y), bfhi(xw.y)}; }
;                 s[q] += (f[q][j].x * f[q][j].x + f[q][j].y * f[q][j].y) + (f[q][j].z * f[q][j].z + f[q][j].w * f[q][j].w);
;             } }
; #pragma unroll
;         for (int q = 0; q < 2; ++q) { const int m = m0 + q * NGW; if (m >= end) break;
;             const float rstd = coef / sqrtf(wave_sum(s[q]) * (1.f / DM) + EPS);
;             float s2 = 0.f;
; #pragma unroll
;             for (int j = 0; j < 4; ++j) { const f32x4 g = ((const f32x4*)post)[lane + 64 * j]; x[q][j] = x[q][j] + f[q][j] * g * rstd; s2 += (x[q][j].x * x[q][j].x + x[q][j].y * x[q][j].y) + (x[q][j].z * x[q][j].z + x[q][j].w * x[q][j].w); }
;             if constexpr (NEXT == 0) {
; #pragma unroll
;                 for (int j = 0; j < 4; ++j) ((f32x4*)((float*)a.in[I_OUT + z] + O_Y + (size_t)m * DM))[lane + 64 * j] = x[q][j];
;             } else {
;                 if constexpr (NEXT == 1) {
; #pragma unroll
;                     for (int j = 0; j < 4; ++j) { u32x2 o; o.x = pk2(x[q][j].x, x[q][j].y); o.y = pk2(x[q][j].z, x[q][j].w); ((u32x2*)(XR + (size_t)m * DM))[lane + 64 * j] = o; }
;                 }
;                 float r2 = 1.f;
;                 if constexpr (NEXT == 1) r2 = 1.f / sqrtf(wave_sum(s2) * (1.f / DM) + EPS);
.LBB0_391:
	global_load_dwordx4 v[56:59], v[40:41], off
	global_load_dwordx4 v[60:63], v[40:41], off offset:1024
	global_load_dwordx4 v[64:67], v[40:41], off offset:2048
	global_load_dwordx4 v[68:71], v[40:41], off offset:3072
	s_waitcnt vmcnt(9)
	v_and_b32_e32 v73, 0xffff0000, v6
	v_and_b32_e32 v75, 0xffff0000, v7
	s_waitcnt vmcnt(8)
	v_and_b32_e32 v77, 0xffff0000, v4
	v_and_b32_e32 v79, 0xffff0000, v5
	v_lshlrev_b32_e32 v72, 16, v6
	v_lshlrev_b32_e32 v74, 16, v7
	v_mul_f32_e32 v6, v73, v73
	v_mul_f32_e32 v7, v75, v75
	v_lshlrev_b32_e32 v76, 16, v4
	v_lshlrev_b32_e32 v78, 16, v5
	v_mul_f32_e32 v4, v77, v77
	v_mul_f32_e32 v5, v79, v79
	s_waitcnt vmcnt(7)
	v_and_b32_e32 v81, 0xffff0000, v2
	v_and_b32_e32 v83, 0xffff0000, v3
	v_fmac_f32_e32 v6, v72, v72
	v_fmac_f32_e32 v7, v74, v74
	v_fmac_f32_e32 v4, v76, v76
	v_fmac_f32_e32 v5, v78, v78
	v_lshlrev_b32_e32 v80, 16, v2
	v_lshlrev_b32_e32 v82, 16, v3
	v_mul_f32_e32 v2, v81, v81
	v_mul_f32_e32 v3, v83, v83
	s_waitcnt vmcnt(6)
	v_and_b32_e32 v85, 0xffff0000, v0
	v_and_b32_e32 v87, 0xffff0000, v1
	v_add_f32_e32 v6, v6, v7
	v_add_f32_e32 v4, v4, v5
	v_fmac_f32_e32 v2, v80, v80
	v_fmac_f32_e32 v3, v82, v82
	v_lshlrev_b32_e32 v84, 16, v0
	v_lshlrev_b32_e32 v86, 16, v1
	v_mul_f32_e32 v0, v85, v85
	v_mul_f32_e32 v1, v87, v87
	v_add_f32_e32 v4, v6, v4
	v_add_f32_e32 v2, v2, v3
	v_fmac_f32_e32 v0, v84, v84
	v_fmac_f32_e32 v1, v86, v86
	v_add_f32_e32 v2, v4, v2
	v_add_f32_e32 v0, v0, v1
	v_add_f32_e32 v0, v2, v0
	s_lshl_b64 s[6:7], s[6:7], 11
	v_lshl_add_u64 v[88:89], v[34:35], 0, s[6:7]
	v_add_f32_dpp v0, v0, v0 quad_perm:[1,0,3,2] row_mask:0xf bank_mask:0xf bound_ctrl:1
	s_waitcnt vmcnt(3)
	v_pk_mul_f32 v[56:57], v[72:73], v[56:57]
	v_add_f32_dpp v0, v0, v0 quad_perm:[2,3,0,1] row_mask:0xf bank_mask:0xf bound_ctrl:1
	v_pk_mul_f32 v[58:59], v[74:75], v[58:59]
	s_nop 0
	v_add_f32_dpp v0, v0, v0 row_half_mirror row_mask:0xf bank_mask:0xf bound_ctrl:1
	s_nop 1
	v_add_f32_dpp v0, v0, v0 row_mirror row_mask:0xf bank_mask:0xf bound_ctrl:1
	v_mov_b32_e32 v1, v0
	s_nop 1
	v_permlane16_swap_b32_e32 v0, v1
	v_add_f32_e32 v0, v0, v1
	v_mov_b32_e32 v1, v0
	s_nop 1
	v_permlane32_swap_b32_e32 v0, v1
	v_add_f32_e32 v0, v0, v1
	v_fmamk_f32 v0, v0, 0x3a800000, v54
	v_mul_f32_e32 v1, 0x4f800000, v0
	v_cmp_gt_f32_e32 vcc, s31, v0
	s_nop 1
	v_cndmask_b32_e32 v8, v0, v1, vcc
	v_sqrt_f32_e32 v9, v8
	global_load_dwordx4 v[4:7], v32, s[24:25]
	global_load_dwordx4 v[0:3], v32, s[24:25] offset:1024
	v_add_u32_e32 v10, -1, v9
	v_fma_f32 v11, -v10, v9, v8
	v_cmp_ge_f32_e64 s[6:7], 0, v11
	v_add_u32_e32 v11, 1, v9
	s_nop 0
	v_cndmask_b32_e64 v10, v9, v10, s[6:7]
	v_fma_f32 v9, -v11, v9, v8
	v_cmp_lt_f32_e64 s[6:7], 0, v9
	s_nop 1
	v_cndmask_b32_e64 v9, v10, v11, s[6:7]
	v_mul_f32_e32 v10, 0x37800000, v9
	v_cndmask_b32_e32 v9, v9, v10, vcc
	v_cmp_class_f32_e32 vcc, v8, v55
	s_nop 1
	v_cndmask_b32_e32 v37, v9, v8, vcc
	v_div_scale_f32 v90, s[6:7], v37, v37, 0.5
	v_rcp_f32_e32 v91, v90
	global_load_dwordx2 v[52:53], v[88:89], off
	global_load_dwordx2 v[50:51], v[88:89], off offset:512
	global_load_dwordx2 v[48:49], v[88:89], off offset:1024
	global_load_dwordx2 v[46:47], v[88:89], off offset:1536
	global_load_dwordx4 v[12:15], v32, s[24:25] offset:2048
	global_load_dwordx4 v[8:11], v32, s[24:25] offset:3072
	v_fma_f32 v88, -v90, v91, 1.0
	v_fmac_f32_e32 v91, v88, v91
	v_div_scale_f32 v88, vcc, 0.5, v37, 0.5
	v_mul_f32_e32 v89, v88, v91
	v_fma_f32 v92, -v90, v89, v88
	v_fmac_f32_e32 v89, v92, v91
	v_fma_f32 v88, -v90, v89, v88
	v_div_fmas_f32 v88, v88, v91, v89
	v_div_fixup_f32 v88, v88, v37, 0.5
	v_pk_fma_f32 v[26:27], v[58:59], v[88:89], v[26:27] op_sel_hi:[1,0,1]
	v_pk_fma_f32 v[24:25], v[56:57], v[88:89], v[24:25] op_sel_hi:[1,0,1]
	s_waitcnt vmcnt(10)
	v_pk_mul_f32 v[56:57], v[76:77], v[60:61]
	v_pk_mul_f32 v[58:59], v[78:79], v[62:63]
	v_pk_fma_f32 v[20:21], v[56:57], v[88:89], v[20:21] op_sel_hi:[1,0,1]
	v_pk_fma_f32 v[22:23], v[58:59], v[88:89], v[22:23] op_sel_hi:[1,0,1]
	s_waitcnt vmcnt(9)
	v_pk_mul_f32 v[56:57], v[80:81], v[64:65]
	v_pk_mul_f32 v[58:59], v[82:83], v[66:67]
	v_pk_fma_f32 v[28:29], v[56:57], v[88:89], v[28:29] op_sel_hi:[1,0,1]
	v_pk_fma_f32 v[30:31], v[58:59], v[88:89], v[30:31] op_sel_hi:[1,0,1]
	s_waitcnt vmcnt(8)
	v_pk_mul_f32 v[56:57], v[84:85], v[68:69]
	v_pk_mul_f32 v[58:59], v[86:87], v[70:71]
	v_pk_fma_f32 v[56:57], v[56:57], v[88:89], v[16:17] op_sel_hi:[1,0,1]
	v_pk_fma_f32 v[58:59], v[58:59], v[88:89], v[18:19] op_sel_hi:[1,0,1]
	v_cvt_pk_bf16_f32 v16, v24, v25
	v_cvt_pk_bf16_f32 v17, v26, v27
	v_lshl_add_u64 v[18:19], v[42:43], 0, s[22:23]
	global_store_dwordx2 v[18:19], v[16:17], off
	v_cvt_pk_bf16_f32 v16, v20, v21
	v_cvt_pk_bf16_f32 v17, v22, v23
	global_store_dwordx2 v[18:19], v[16:17], off offset:512
	v_cvt_pk_bf16_f32 v16, v28, v29
	v_cvt_pk_bf16_f32 v17, v30, v31
	global_store_dwordx2 v[18:19], v[16:17], off offset:1024
	v_cvt_pk_bf16_f32 v16, v56, v57
	v_cvt_pk_bf16_f32 v17, v58, v59
	global_store_dwordx2 v[18:19], v[16:17], off offset:1536
	s_nop 1
	v_mov_b64_e32 v[16:17], v[100:101]
	v_mov_b64_e32 v[18:19], v[102:103]
	v_mul_f32_e32 v61, v21, v21
	v_mul_f32_e32 v62, v23, v23
	v_fmac_f32_e32 v61, v20, v20
	v_fmac_f32_e32 v62, v22, v22
	v_mul_f32_e32 v37, v25, v25
	v_mul_f32_e32 v60, v27, v27
	v_add_f32_e32 v61, v61, v62
	v_mul_f32_e32 v62, v29, v29
	v_mul_f32_e32 v63, v31, v31
	v_fmac_f32_e32 v60, v26, v26
	v_fmac_f32_e32 v62, v28, v28
	v_fmac_f32_e32 v63, v30, v30
	v_fmac_f32_e32 v37, v24, v24
	v_add_f32_e32 v62, v62, v63
	v_mul_f32_e32 v63, v57, v57
	v_mul_f32_e32 v64, v59, v59
	v_add_f32_e32 v37, v37, v60
	v_fmac_f32_e32 v63, v56, v56
	v_fmac_f32_e32 v64, v58, v58
	v_add_f32_e32 v37, v37, v61
; __device__ __forceinline__ float bflo(unsigned w) { return __uint_as_float(w << 16); }
; __device__ __forceinline__ float bfhi(unsigned w) { return __uint_as_float(w & 0xffff0000u); }
; __device__ __forceinline__ unsigned pk2(float lo, float hi) { f32x2 v = {lo, hi}; bf16x2_t b = __builtin_convertvector(v, bf16x2_t); return __builtin_bit_cast(unsigned, b); }
; template <int NEXT, int SRC> __device__ __forceinline__ void norm_rows(const Args& a, const bf16* Fin, float coef, int i_post, int i_pre, int first, int NGW, int end, int lane) {
;     ...
;         for (int q = 0; q < 2; ++q) { const int m = m0 + q * NGW; const bool ok = m < end; const int mm = ok ? m : m0;
;             const float* xr = SRC == 0 ? xrow_ptr(a, mm, z) : nullptr;
;             const bf16* xb = (SRC == 1 ? XR : XN) + (size_t)mm * DM;
; #pragma unroll
;             for (int j = 0; j < 4; ++j) {
;                 const u32x2 w = ((const u32x2*)(Fin + (size_t)mm * DM))[lane + 64 * j];
;                 f[q][j] = (f32x4){bflo(w.x), bfhi(w.x), bflo(w.y), bfhi(w.y)};
;                 if constexpr (SRC == 0) x[q][j] = ((const f32x4*)xr)[lane + 64 * j];
;                 else { const u32x2 xw = ((const u32x2*)xb)[lane + 64 * j]; x[q][j] = (f32x4){bflo(xw.x), bfhi(xw.x), bflo(xw.y), bfhi(xw.y)}; }
;                 s[q] += (f[q][j].x * f[q][j].x + f[q][j].y * f[q][j].y) + (f[q][j].z * f[q][j].z + f[q][j].w * f[q][j].w);
;             } }
;     ...
;                 float r2 = 1.f;
;                 if constexpr (NEXT == 1) r2 = 1.f / sqrtf(wave_sum(s2) * (1.f / DM) + EPS);
; #pragma unroll
;                 for (int j = 0; j < 4; ++j) {
;                     f32x4 g = {1.f, 1.f, 1.f, 1.f};
;                     if constexpr (NEXT == 1) g = ((const f32x4*)pre)[lane + 64 * j];
;                     u32x2 o; o.x = pk2(x[q][j].x * r2 * g.x, x[q][j].y * r2 * g.y); o.y = pk2(x[q][j].z * r2 * g.z, x[q][j].w * r2 * g.w);
;                     ((u32x2*)(XN + (size_t)m * DM))[lane + 64 * j] = o;
;                 }
	v_add_f32_e32 v63, v63, v64
	v_add_f32_e32 v37, v62, v37
	v_add_f32_e32 v37, v63, v37
	s_nop 1
	v_add_f32_dpp v37, v37, v37 quad_perm:[1,0,3,2] row_mask:0xf bank_mask:0xf bound_ctrl:1
	s_nop 1
	v_add_f32_dpp v37, v37, v37 quad_perm:[2,3,0,1] row_mask:0xf bank_mask:0xf bound_ctrl:1
	s_nop 1
	v_add_f32_dpp v37, v37, v37 row_half_mirror row_mask:0xf bank_mask:0xf bound_ctrl:1
	s_nop 1
	v_add_f32_dpp v37, v37, v37 row_mirror row_mask:0xf bank_mask:0xf bound_ctrl:1
	v_mov_b32_e32 v60, v37
	s_nop 1
	v_permlane16_swap_b32_e32 v37, v60
	v_add_f32_e32 v37, v37, v60
	v_mov_b32_e32 v60, v37
	s_nop 1
	v_permlane32_swap_b32_e32 v37, v60
	v_add_f32_e32 v37, v37, v60
	v_fmamk_f32 v37, v37, 0x3a800000, v54
	v_mul_f32_e32 v60, 0x4f800000, v37
	v_cmp_gt_f32_e32 vcc, s31, v37
	s_nop 1
	v_cndmask_b32_e32 v37, v37, v60, vcc
	v_sqrt_f32_e32 v60, v37
	s_nop 0
	v_add_u32_e32 v61, -1, v60
	v_fma_f32 v62, -v61, v60, v37
	v_cmp_ge_f32_e64 s[6:7], 0, v62
	v_add_u32_e32 v62, 1, v60
	s_nop 0
	v_cndmask_b32_e64 v61, v60, v61, s[6:7]
	v_fma_f32 v60, -v62, v60, v37
	v_cmp_lt_f32_e64 s[6:7], 0, v60
	s_nop 1
	v_cndmask_b32_e64 v60, v61, v62, s[6:7]
	v_mul_f32_e32 v61, 0x37800000, v60
	v_cndmask_b32_e32 v60, v60, v61, vcc
	v_cmp_class_f32_e32 vcc, v37, v55
	s_nop 1
	v_cndmask_b32_e32 v37, v60, v37, vcc
	v_div_scale_f32 v60, s[6:7], v37, v37, 1.0
	v_rcp_f32_e32 v61, v60
	s_nop 0
	v_fma_f32 v62, -v60, v61, 1.0
	v_fmac_f32_e32 v61, v62, v61
	v_div_scale_f32 v62, vcc, 1.0, v37, 1.0
	v_mul_f32_e32 v63, v62, v61
	v_fma_f32 v64, -v60, v63, v62
	v_fmac_f32_e32 v63, v64, v61
	v_fma_f32 v60, -v60, v63, v62
	v_div_fmas_f32 v60, v60, v61, v63
	v_div_fixup_f32 v60, v60, v37, 1.0
	v_pk_mul_f32 v[24:25], v[24:25], v[60:61] op_sel_hi:[1,0]
	v_pk_mul_f32 v[20:21], v[20:21], v[60:61] op_sel_hi:[1,0]
	s_waitcnt vmcnt(4)
	v_pk_mul_f32 v[16:17], v[16:17], v[24:25]
	v_pk_mul_f32 v[24:25], v[26:27], v[60:61] op_sel_hi:[1,0]
	v_cvt_pk_bf16_f32 v16, v16, v17
	v_pk_mul_f32 v[18:19], v[18:19], v[24:25]
	v_lshl_add_u64 v[24:25], v[44:45], 0, s[22:23]
	v_cvt_pk_bf16_f32 v17, v18, v19
	global_store_dwordx2 v[24:25], v[16:17], off
	s_nop 1
	v_mov_b64_e32 v[16:17], v[104:105]
	v_mov_b64_e32 v[18:19], v[106:107]
	v_pk_mul_f32 v[22:23], v[22:23], v[60:61] op_sel_hi:[1,0]
	s_andn2_b64 vcc, exec, s[20:21]
	v_pk_mul_f32 v[16:17], v[16:17], v[20:21]
	v_pk_mul_f32 v[18:19], v[18:19], v[22:23]
	v_cvt_pk_bf16_f32 v16, v16, v17
	v_cvt_pk_bf16_f32 v17, v18, v19
	global_store_dwordx2 v[24:25], v[16:17], off offset:512
	s_nop 1
	v_mov_b64_e32 v[16:17], v[108:109]
	v_mov_b64_e32 v[18:19], v[110:111]
	v_pk_mul_f32 v[20:21], v[28:29], v[60:61] op_sel_hi:[1,0]
	v_pk_mul_f32 v[22:23], v[30:31], v[60:61] op_sel_hi:[1,0]
	v_pk_mul_f32 v[16:17], v[16:17], v[20:21]
	v_pk_mul_f32 v[18:19], v[18:19], v[22:23]
	v_cvt_pk_bf16_f32 v16, v16, v17
	v_cvt_pk_bf16_f32 v17, v18, v19
	global_store_dwordx2 v[24:25], v[16:17], off offset:1024
	s_nop 1
	v_mov_b64_e32 v[16:17], v[112:113]
	v_mov_b64_e32 v[18:19], v[114:115]
	v_pk_mul_f32 v[20:21], v[56:57], v[60:61] op_sel_hi:[1,0]
	v_pk_mul_f32 v[22:23], v[58:59], v[60:61] op_sel_hi:[1,0]
	v_pk_mul_f32 v[16:17], v[16:17], v[20:21]
	v_pk_mul_f32 v[18:19], v[18:19], v[22:23]
	v_cvt_pk_bf16_f32 v16, v16, v17
	v_cvt_pk_bf16_f32 v17, v18, v19
	global_store_dwordx2 v[24:25], v[16:17], off offset:1536
	s_cbranch_vccnz .LBB0_382
	v_lshlrev_b32_e32 v56, 16, v52
	v_and_b32_e32 v57, 0xffff0000, v52
	v_lshlrev_b32_e32 v52, 16, v53
	v_and_b32_e32 v53, 0xffff0000, v53
	v_mul_f32_e32 v16, v57, v57
	v_mul_f32_e32 v17, v53, v53
	v_fmac_f32_e32 v16, v56, v56
	v_fmac_f32_e32 v17, v52, v52
	v_lshlrev_b32_e32 v58, 16, v50
	v_and_b32_e32 v59, 0xffff0000, v50
	v_lshlrev_b32_e32 v50, 16, v51
	v_and_b32_e32 v51, 0xffff0000, v51
	v_add_f32_e32 v28, v16, v17
	v_mul_f32_e32 v24, v59, v59
	global_load_dwordx4 v[16:19], v[40:41], off
	global_load_dwordx4 v[20:23], v[40:41], off offset:1024
	v_mul_f32_e32 v25, v51, v51
	v_fmac_f32_e32 v24, v58, v58
	v_fmac_f32_e32 v25, v50, v50
	v_add_f32_e32 v29, v24, v25
	global_load_dwordx4 v[24:27], v[40:41], off offset:2048
	v_add_f32_e32 v37, v28, v29
	global_load_dwordx4 v[28:31], v[40:41], off offset:3072
	v_lshlrev_b32_e32 v60, 16, v48
	v_and_b32_e32 v61, 0xffff0000, v48
	v_lshlrev_b32_e32 v48, 16, v49
	v_and_b32_e32 v49, 0xffff0000, v49
	v_mul_f32_e32 v62, v61, v61
	v_mul_f32_e32 v63, v49, v49
	v_fmac_f32_e32 v62, v60, v60
	v_fmac_f32_e32 v63, v48, v48
	v_add_f32_e32 v62, v62, v63
	v_add_f32_e32 v37, v37, v62
	v_lshlrev_b32_e32 v62, 16, v46
	v_and_b32_e32 v63, 0xffff0000, v46
	v_lshlrev_b32_e32 v46, 16, v47
	v_and_b32_e32 v47, 0xffff0000, v47
	v_mul_f32_e32 v64, v63, v63
	v_mul_f32_e32 v65, v47, v47
	v_fmac_f32_e32 v64, v62, v62
	v_fmac_f32_e32 v65, v46, v46
	v_add_f32_e32 v64, v64, v65
	v_add_f32_e32 v37, v37, v64
	s_waitcnt vmcnt(3)
; __device__ __forceinline__ unsigned pk2(float lo, float hi) { f32x2 v = {lo, hi}; bf16x2_t b = __builtin_convertvector(v, bf16x2_t); return __builtin_bit_cast(unsigned, b); }
; template <int NEXT, int SRC> __device__ __forceinline__ void norm_rows(const Args& a, const bf16* Fin, float coef, int i_post, int i_pre, int first, int NGW, int end, int lane) {
;     ...
; #pragma unroll
;         for (int q = 0; q < 2; ++q) { const int m = m0 + q * NGW; if (m >= end) break;
;             const float rstd = coef / sqrtf(wave_sum(s[q]) * (1.f / DM) + EPS);
;             float s2 = 0.f;
; #pragma unroll
;             for (int j = 0; j < 4; ++j) { const f32x4 g = ((const f32x4*)post)[lane + 64 * j]; x[q][j] = x[q][j] + f[q][j] * g * rstd; s2 += (x[q][j].x * x[q][j].x + x[q][j].y * x[q][j].y) + (x[q][j].z * x[q][j].z + x[q][j].w * x[q][j].w); }
;             if constexpr (NEXT == 0) {
; #pragma unroll
;                 for (int j = 0; j < 4; ++j) ((f32x4*)((float*)a.in[I_OUT + z] + O_Y + (size_t)m * DM))[lane + 64 * j] = x[q][j];
;             } else {
;                 if constexpr (NEXT == 1) {
; #pragma unroll
;                     for (int j = 0; j < 4; ++j) { u32x2 o; o.x = pk2(x[q][j].x, x[q][j].y); o.y = pk2(x[q][j].z, x[q][j].w); ((u32x2*)(XR + (size_t)m * DM))[lane + 64 * j] = o; }
;                 }
;                 float r2 = 1.f;
;                 if constexpr (NEXT == 1) r2 = 1.f / sqrtf(wave_sum(s2) * (1.f / DM) + EPS);
; #pragma unroll
;                 for (int j = 0; j < 4; ++j) {
;                     f32x4 g = {1.f, 1.f, 1.f, 1.f};
;                     if constexpr (NEXT == 1) g = ((const f32x4*)pre)[lane + 64 * j];
;                     u32x2 o; o.x = pk2(x[q][j].x * r2 * g.x, x[q][j].y * r2 * g.y); o.y = pk2(x[q][j].z * r2 * g.z, x[q][j].w * r2 * g.w);
;                     ((u32x2*)(XN + (size_t)m * DM))[lane + 64 * j] = o;
;                 }
	v_pk_mul_f32 v[16:17], v[56:57], v[16:17]
	v_add_f32_dpp v37, v37, v37 quad_perm:[1,0,3,2] row_mask:0xf bank_mask:0xf bound_ctrl:1
	v_pk_mul_f32 v[18:19], v[52:53], v[18:19]
	s_nop 0
	v_add_f32_dpp v37, v37, v37 quad_perm:[2,3,0,1] row_mask:0xf bank_mask:0xf bound_ctrl:1
	s_nop 1
	v_add_f32_dpp v37, v37, v37 row_half_mirror row_mask:0xf bank_mask:0xf bound_ctrl:1
	s_nop 1
	v_add_f32_dpp v37, v37, v37 row_mirror row_mask:0xf bank_mask:0xf bound_ctrl:1
	v_mov_b32_e32 v64, v37
	s_nop 1
	v_permlane16_swap_b32_e32 v37, v64
	v_add_f32_e32 v37, v37, v64
	v_mov_b32_e32 v64, v37
	s_nop 1
	v_permlane32_swap_b32_e32 v37, v64
	v_add_f32_e32 v37, v37, v64
	v_fmamk_f32 v37, v37, 0x3a800000, v54
	v_mul_f32_e32 v64, 0x4f800000, v37
	v_cmp_gt_f32_e32 vcc, s31, v37
	s_nop 1
	v_cndmask_b32_e32 v37, v37, v64, vcc
	v_sqrt_f32_e32 v64, v37
	s_nop 0
	v_add_u32_e32 v65, -1, v64
	v_fma_f32 v66, -v65, v64, v37
	v_cmp_ge_f32_e64 s[6:7], 0, v66
	v_add_u32_e32 v66, 1, v64
	s_nop 0
	v_cndmask_b32_e64 v65, v64, v65, s[6:7]
	v_fma_f32 v64, -v66, v64, v37
	v_cmp_lt_f32_e64 s[6:7], 0, v64
	s_nop 1
	v_cndmask_b32_e64 v64, v65, v66, s[6:7]
	v_mul_f32_e32 v65, 0x37800000, v64
	v_cndmask_b32_e32 v64, v64, v65, vcc
	v_cmp_class_f32_e32 vcc, v37, v55
	s_nop 1
	v_cndmask_b32_e32 v37, v64, v37, vcc
	v_div_scale_f32 v64, s[6:7], v37, v37, 0.5
	v_rcp_f32_e32 v65, v64
	s_add_i32 s6, s0, 0x4008
	s_ashr_i32 s7, s6, 31
	s_lshl_b64 s[20:21], s[6:7], 11
	v_fma_f32 v66, -v64, v65, 1.0
	v_fmac_f32_e32 v65, v66, v65
	v_div_scale_f32 v66, vcc, 0.5, v37, 0.5
	v_mul_f32_e32 v67, v66, v65
	v_fma_f32 v68, -v64, v67, v66
	v_fmac_f32_e32 v67, v68, v65
	v_fma_f32 v64, -v64, v67, v66
	v_div_fmas_f32 v64, v64, v65, v67
	v_div_fixup_f32 v64, v64, v37, 0.5
	v_pk_fma_f32 v[6:7], v[18:19], v[64:65], v[6:7] op_sel_hi:[1,0,1]
	v_pk_fma_f32 v[4:5], v[16:17], v[64:65], v[4:5] op_sel_hi:[1,0,1]
	s_waitcnt vmcnt(2)
	v_pk_mul_f32 v[16:17], v[58:59], v[20:21]
	v_pk_mul_f32 v[18:19], v[50:51], v[22:23]
	v_pk_fma_f32 v[16:17], v[16:17], v[64:65], v[0:1] op_sel_hi:[1,0,1]
	v_pk_fma_f32 v[18:19], v[18:19], v[64:65], v[2:3] op_sel_hi:[1,0,1]
	s_waitcnt vmcnt(1)
	v_pk_mul_f32 v[0:1], v[60:61], v[24:25]
	v_pk_mul_f32 v[2:3], v[48:49], v[26:27]
	v_pk_fma_f32 v[12:13], v[0:1], v[64:65], v[12:13] op_sel_hi:[1,0,1]
	v_pk_fma_f32 v[14:15], v[2:3], v[64:65], v[14:15] op_sel_hi:[1,0,1]
	s_waitcnt vmcnt(0)
	v_pk_mul_f32 v[0:1], v[62:63], v[28:29]
	v_pk_mul_f32 v[2:3], v[46:47], v[30:31]
	v_pk_fma_f32 v[8:9], v[0:1], v[64:65], v[8:9] op_sel_hi:[1,0,1]
	v_pk_fma_f32 v[10:11], v[2:3], v[64:65], v[10:11] op_sel_hi:[1,0,1]
	v_cvt_pk_bf16_f32 v0, v4, v5
	v_cvt_pk_bf16_f32 v1, v6, v7
	v_lshl_add_u64 v[2:3], v[42:43], 0, s[20:21]
	global_store_dwordx2 v[2:3], v[0:1], off
	v_cvt_pk_bf16_f32 v0, v16, v17
	v_cvt_pk_bf16_f32 v1, v18, v19
	global_store_dwordx2 v[2:3], v[0:1], off offset:512
	v_cvt_pk_bf16_f32 v0, v12, v13
	v_cvt_pk_bf16_f32 v1, v14, v15
	global_store_dwordx2 v[2:3], v[0:1], off offset:1024
	v_cvt_pk_bf16_f32 v0, v8, v9
	v_cvt_pk_bf16_f32 v1, v10, v11
	global_store_dwordx2 v[2:3], v[0:1], off offset:1536
	s_nop 1
	v_mov_b64_e32 v[0:1], v[100:101]
	v_mov_b64_e32 v[2:3], v[102:103]
	v_mul_f32_e32 v22, v17, v17
	v_mul_f32_e32 v23, v19, v19
	v_fmac_f32_e32 v22, v16, v16
	v_fmac_f32_e32 v23, v18, v18
	v_mul_f32_e32 v20, v5, v5
	v_mul_f32_e32 v21, v7, v7
	v_add_f32_e32 v22, v22, v23
	v_mul_f32_e32 v23, v13, v13
	v_mul_f32_e32 v24, v15, v15
	v_fmac_f32_e32 v21, v6, v6
	v_fmac_f32_e32 v23, v12, v12
	v_fmac_f32_e32 v24, v14, v14
	v_fmac_f32_e32 v20, v4, v4
	v_add_f32_e32 v23, v23, v24
	v_mul_f32_e32 v24, v9, v9
	v_mul_f32_e32 v25, v11, v11
	v_add_f32_e32 v20, v20, v21
	v_fmac_f32_e32 v24, v8, v8
	v_fmac_f32_e32 v25, v10, v10
	v_add_f32_e32 v20, v20, v22
	v_add_f32_e32 v24, v24, v25
	v_add_f32_e32 v20, v23, v20
	v_add_f32_e32 v20, v24, v20
	s_nop 1
	v_add_f32_dpp v20, v20, v20 quad_perm:[1,0,3,2] row_mask:0xf bank_mask:0xf bound_ctrl:1
	s_nop 1
	v_add_f32_dpp v20, v20, v20 quad_perm:[2,3,0,1] row_mask:0xf bank_mask:0xf bound_ctrl:1
	s_nop 1
	v_add_f32_dpp v20, v20, v20 row_half_mirror row_mask:0xf bank_mask:0xf bound_ctrl:1
	s_nop 1
	v_add_f32_dpp v20, v20, v20 row_mirror row_mask:0xf bank_mask:0xf bound_ctrl:1
	v_mov_b32_e32 v21, v20
	s_nop 1
	v_permlane16_swap_b32_e32 v20, v21
	v_add_f32_e32 v20, v20, v21
	v_mov_b32_e32 v21, v20
	s_nop 1
	v_permlane32_swap_b32_e32 v20, v21
	v_add_f32_e32 v20, v20, v21
	v_fmamk_f32 v20, v20, 0x3a800000, v54
	v_mul_f32_e32 v21, 0x4f800000, v20
	v_cmp_gt_f32_e32 vcc, s31, v20
	s_nop 1
	v_cndmask_b32_e32 v20, v20, v21, vcc
	v_sqrt_f32_e32 v21, v20
	s_nop 0
	v_add_u32_e32 v22, -1, v21
	v_fma_f32 v23, -v22, v21, v20
	v_cmp_ge_f32_e64 s[6:7], 0, v23
	v_add_u32_e32 v23, 1, v21
	s_nop 0
	v_cndmask_b32_e64 v22, v21, v22, s[6:7]
	v_fma_f32 v21, -v23, v21, v20
	v_cmp_lt_f32_e64 s[6:7], 0, v21
	s_nop 1
	v_cndmask_b32_e64 v21, v22, v23, s[6:7]
	v_mul_f32_e32 v22, 0x37800000, v21
	v_cndmask_b32_e32 v21, v21, v22, vcc
	v_cmp_class_f32_e32 vcc, v20, v55
	s_nop 1
	v_cndmask_b32_e32 v20, v21, v20, vcc
	v_div_scale_f32 v21, s[6:7], v20, v20, 1.0
	v_rcp_f32_e32 v22, v21
	s_nop 0
	v_fma_f32 v23, -v21, v22, 1.0
	v_fmac_f32_e32 v22, v23, v22
	v_div_scale_f32 v23, vcc, 1.0, v20, 1.0
	v_mul_f32_e32 v24, v23, v22
	v_fma_f32 v25, -v21, v24, v23
	v_fmac_f32_e32 v24, v25, v22
	v_fma_f32 v21, -v21, v24, v23
	v_div_fmas_f32 v21, v21, v22, v24
	v_div_fixup_f32 v20, v21, v20, 1.0
	v_pk_mul_f32 v[4:5], v[4:5], v[20:21] op_sel_hi:[1,0]
	v_pk_mul_f32 v[0:1], v[0:1], v[4:5]
	v_pk_mul_f32 v[4:5], v[6:7], v[20:21] op_sel_hi:[1,0]
	v_cvt_pk_bf16_f32 v0, v0, v1
	v_pk_mul_f32 v[2:3], v[2:3], v[4:5]
	v_lshl_add_u64 v[4:5], v[44:45], 0, s[20:21]
	v_cvt_pk_bf16_f32 v1, v2, v3
	global_store_dwordx2 v[4:5], v[0:1], off
	s_nop 1
	v_mov_b64_e32 v[0:1], v[104:105]
	v_mov_b64_e32 v[2:3], v[106:107]
	v_pk_mul_f32 v[6:7], v[16:17], v[20:21] op_sel_hi:[1,0]
	v_pk_mul_f32 v[16:17], v[18:19], v[20:21] op_sel_hi:[1,0]
	v_pk_mul_f32 v[0:1], v[0:1], v[6:7]
	v_pk_mul_f32 v[2:3], v[2:3], v[16:17]
	v_cvt_pk_bf16_f32 v0, v0, v1
	v_cvt_pk_bf16_f32 v1, v2, v3
	global_store_dwordx2 v[4:5], v[0:1], off offset:512
	s_nop 1
	v_mov_b64_e32 v[0:1], v[108:109]
	v_mov_b64_e32 v[2:3], v[110:111]
	v_pk_mul_f32 v[6:7], v[12:13], v[20:21] op_sel_hi:[1,0]
	v_pk_mul_f32 v[12:13], v[14:15], v[20:21] op_sel_hi:[1,0]
	v_pk_mul_f32 v[0:1], v[0:1], v[6:7]
	v_pk_mul_f32 v[2:3], v[2:3], v[12:13]
	v_cvt_pk_bf16_f32 v0, v0, v1
	v_cvt_pk_bf16_f32 v1, v2, v3
	global_store_dwordx2 v[4:5], v[0:1], off offset:1024
	s_nop 1
	v_mov_b64_e32 v[0:1], v[112:113]
	v_mov_b64_e32 v[2:3], v[114:115]
	v_pk_mul_f32 v[6:7], v[8:9], v[20:21] op_sel_hi:[1,0]
	v_pk_mul_f32 v[8:9], v[10:11], v[20:21] op_sel_hi:[1,0]
	v_pk_mul_f32 v[0:1], v[0:1], v[6:7]
	v_pk_mul_f32 v[2:3], v[2:3], v[8:9]
	v_cvt_pk_bf16_f32 v0, v0, v1
	v_cvt_pk_bf16_f32 v1, v2, v3
	global_store_dwordx2 v[4:5], v[0:1], off offset:1536
	s_branch .LBB0_382

; __device__ __forceinline__ float bflo(unsigned w) { return __uint_as_float(w << 16); }
; __device__ __forceinline__ float bfhi(unsigned w) { return __uint_as_float(w & 0xffff0000u); }
; template <int NEXT, int SRC> __device__ __forceinline__ void norm_rows(const Args& a, const bf16* Fin, float coef, int i_post, int i_pre, int first, int NGW, int end, int lane) {
;     ...
;     for (int m0 = first; m0 < end; m0 += 2 * NGW) {
;         f32x4 f[2][4], x[2][4]; float s[2] = {0.f, 0.f};
; #pragma unroll
;         for (int q = 0; q < 2; ++q) { const int m = m0 + q * NGW; const bool ok = m < end; const int mm = ok ? m : m0;
;             const float* xr = SRC == 0 ? xrow_ptr(a, mm, z) : nullptr;
;             const bf16* xb = (SRC == 1 ? XR : XN) + (size_t)mm * DM;
; #pragma unroll
;             for (int j = 0; j < 4; ++j) {
;                 const u32x2 w = ((const u32x2*)(Fin + (size_t)mm * DM))[lane + 64 * j];
;                 f[q][j] = (f32x4){bflo(w.x), bfhi(w.x), bflo(w.y), bfhi(w.y)};
;                 if constexpr (SRC == 0) x[q][j] = ((const f32x4*)xr)[lane + 64 * j];
;                 else { const u32x2 xw = ((const u32x2*)xb)[lane + 64 * j]; x[q][j] = (f32x4){bflo(xw.x), bfhi(xw.x), bflo(xw.y), bfhi(xw.y)}; }
;                 s[q] += (f[q][j].x * f[q][j].x + f[q][j].y * f[q][j].y) + (f[q][j].z * f[q][j].z + f[q][j].w * f[q][j].w);
;             } }
; #pragma unroll
;         for (int q = 0; q < 2; ++q) { const int m = m0 + q * NGW; if (m >= end) break;
;             const float rstd = coef / sqrtf(wave_sum(s[q]) * (1.f / DM) + EPS);
;             float s2 = 0.f;
; #pragma unroll
;             for (int j = 0; j < 4; ++j) { const f32x4 g = ((const f32x4*)post)[lane + 64 * j]; x[q][j] = x[q][j] + f[q][j] * g * rstd; s2 += (x[q][j].x * x[q][j].x + x[q][j].y * x[q][j].y) + (x[q][j].z * x[q][j].z + x[q][j].w * x[q][j].w); }
.LBB0_1721:
	v_lshl_add_u64 v[14:15], s[14:15], 0, v[2:3]
	v_add_co_u32_e32 v14, vcc, s22, v14
	v_lshl_add_u64 v[26:27], s[12:13], 0, v[2:3]
	s_nop 0
	v_addc_co_u32_e32 v15, vcc, 0, v15, vcc
	v_add_co_u32_e32 v32, vcc, s23, v26
	global_load_dwordx4 v[100:103], v[8:9], off
	global_load_dwordx4 v[104:107], v[8:9], off offset:1024
	global_load_dwordx4 v[108:111], v[8:9], off offset:2048
	global_load_dwordx4 v[112:115], v[8:9], off offset:3072
	global_load_dwordx2 v[52:53], v[14:15], off
	global_load_dwordx2 v[54:55], v[14:15], off offset:512
	global_load_dwordx2 v[56:57], v[14:15], off offset:1024
	v_addc_co_u32_e32 v33, vcc, 0, v27, vcc
	global_load_dwordx2 v[58:59], v[14:15], off offset:1536
	global_load_dwordx2 v[60:61], v[32:33], off offset:1536
	global_load_dwordx2 v[62:63], v[32:33], off offset:1024
	global_load_dwordx2 v[64:65], v[32:33], off offset:512
	global_load_dwordx4 v[36:39], v[10:11], off
	global_load_dwordx4 v[40:43], v[10:11], off offset:1024
	global_load_dwordx4 v[44:47], v[10:11], off offset:2048
	global_load_dwordx4 v[48:51], v[10:11], off offset:3072
	global_load_dwordx2 v[66:67], v[32:33], off
	s_add_i32 s11, s10, 8
	s_cmp_lt_i32 s11, s26
	s_cselect_b32 s6, s11, s10
	s_ashr_i32 s7, s6, 31
	s_lshl_b64 s[6:7], s[6:7], 11
	v_lshl_add_u64 v[68:69], v[4:5], 0, s[6:7]
	v_lshl_add_u64 v[70:71], v[12:13], 0, s[6:7]
	global_load_dwordx2 v[30:31], v[68:69], off
	global_load_dwordx2 v[28:29], v[68:69], off offset:512
	global_load_dwordx2 v[24:25], v[68:69], off offset:1024
	global_load_dwordx2 v[22:23], v[68:69], off offset:1536
	global_load_dwordx2 v[14:15], v[70:71], off
	global_load_dwordx2 v[16:17], v[70:71], off offset:512
	global_load_dwordx2 v[18:19], v[70:71], off offset:1024
	global_load_dwordx2 v[20:21], v[70:71], off offset:1536
	s_cmp_ge_i32 s11, s26
	s_waitcnt vmcnt(19)
	v_lshlrev_b32_e32 v68, 16, v52
	v_and_b32_e32 v69, 0xffff0000, v52
	v_lshlrev_b32_e32 v52, 16, v53
	v_and_b32_e32 v53, 0xffff0000, v53
	s_waitcnt vmcnt(18)
	v_lshlrev_b32_e32 v70, 16, v54
	v_and_b32_e32 v71, 0xffff0000, v54
	v_lshlrev_b32_e32 v54, 16, v55
	v_and_b32_e32 v55, 0xffff0000, v55
	s_waitcnt vmcnt(17)
	v_lshlrev_b32_e32 v72, 16, v56
	v_and_b32_e32 v73, 0xffff0000, v56
	v_lshlrev_b32_e32 v56, 16, v57
	v_and_b32_e32 v57, 0xffff0000, v57
	s_waitcnt vmcnt(13)
	v_lshlrev_b32_e32 v80, 16, v64
	v_and_b32_e32 v81, 0xffff0000, v64
	v_mul_f32_e32 v7, v69, v69
	v_mul_f32_e32 v64, v53, v53
	v_mul_f32_e32 v82, v71, v71
	v_mul_f32_e32 v83, v55, v55
	v_lshlrev_b32_e32 v74, 16, v58
	v_and_b32_e32 v75, 0xffff0000, v58
	v_lshlrev_b32_e32 v58, 16, v59
	v_and_b32_e32 v59, 0xffff0000, v59
	v_mul_f32_e32 v84, v73, v73
	v_mul_f32_e32 v85, v57, v57
	v_fmac_f32_e32 v7, v68, v68
	v_fmac_f32_e32 v64, v52, v52
	v_fmac_f32_e32 v82, v70, v70
	v_fmac_f32_e32 v83, v54, v54
	v_mul_f32_e32 v86, v75, v75
	v_mul_f32_e32 v87, v59, v59
	v_fmac_f32_e32 v84, v72, v72
	v_fmac_f32_e32 v85, v56, v56
	v_add_f32_e32 v7, v7, v64
	v_add_f32_e32 v64, v82, v83
	v_fmac_f32_e32 v86, v74, v74
	v_fmac_f32_e32 v87, v58, v58
	v_add_f32_e32 v82, v84, v85
	v_add_f32_e32 v7, v7, v64
	v_add_f32_e32 v83, v86, v87
	v_add_f32_e32 v7, v7, v82
	v_add_f32_e32 v7, v7, v83
	s_waitcnt vmcnt(8)
	v_lshlrev_b32_e32 v82, 16, v66
	v_pk_mul_f32 v[36:37], v[68:69], v[36:37]
	v_add_f32_dpp v7, v7, v7 quad_perm:[1,0,3,2] row_mask:0xf bank_mask:0xf bound_ctrl:1
	v_pk_mul_f32 v[38:39], v[52:53], v[38:39]
	v_lshlrev_b32_e32 v78, 16, v62
	v_add_f32_dpp v7, v7, v7 quad_perm:[2,3,0,1] row_mask:0xf bank_mask:0xf bound_ctrl:1
	v_and_b32_e32 v79, 0xffff0000, v62
	v_lshlrev_b32_e32 v76, 16, v60
	v_add_f32_dpp v7, v7, v7 row_half_mirror row_mask:0xf bank_mask:0xf bound_ctrl:1
	v_and_b32_e32 v77, 0xffff0000, v60
	v_lshlrev_b32_e32 v62, 16, v63
	v_add_f32_dpp v7, v7, v7 row_mirror row_mask:0xf bank_mask:0xf bound_ctrl:1
	v_mov_b32_e32 v64, v7
	s_nop 1
	v_permlane16_swap_b32_e32 v7, v64
	v_add_f32_e32 v7, v7, v64
	v_mov_b32_e32 v64, v7
	s_nop 1
	v_permlane32_swap_b32_e32 v7, v64
	v_add_f32_e32 v7, v7, v64
	v_fmamk_f32 v7, v7, 0x3a800000, v34
	v_mul_f32_e32 v64, 0x4f800000, v7
	v_cmp_gt_f32_e32 vcc, s24, v7
	v_and_b32_e32 v63, 0xffff0000, v63
	v_lshlrev_b32_e32 v60, 16, v61
	v_cndmask_b32_e32 v7, v7, v64, vcc
	v_sqrt_f32_e32 v83, v7
	v_lshlrev_b32_e32 v64, 16, v65
	v_and_b32_e32 v65, 0xffff0000, v65
	v_and_b32_e32 v61, 0xffff0000, v61
	v_add_u32_e32 v84, -1, v83
	v_fma_f32 v85, -v84, v83, v7
	v_cmp_ge_f32_e64 s[6:7], 0, v85
	v_add_u32_e32 v85, 1, v83
	s_nop 0
	v_cndmask_b32_e64 v84, v83, v84, s[6:7]
	v_fma_f32 v83, -v85, v83, v7
	v_cmp_lt_f32_e64 s[6:7], 0, v83
	s_nop 1
	v_cndmask_b32_e64 v83, v84, v85, s[6:7]
	v_mul_f32_e32 v84, 0x37800000, v83
	v_cndmask_b32_e32 v83, v83, v84, vcc
	v_cmp_class_f32_e32 vcc, v7, v35
	s_nop 1
	v_cndmask_b32_e32 v7, v83, v7, vcc
	v_div_scale_f32 v84, s[6:7], v7, v7, 1.0
	v_rcp_f32_e32 v85, v84
	v_and_b32_e32 v83, 0xffff0000, v66
	v_lshlrev_b32_e32 v66, 16, v67
	v_and_b32_e32 v67, 0xffff0000, v67
	v_fma_f32 v86, -v84, v85, 1.0
	v_fmac_f32_e32 v85, v86, v85
	v_div_scale_f32 v86, vcc, 1.0, v7, 1.0
	v_mul_f32_e32 v87, v86, v85
	v_fma_f32 v88, -v84, v87, v86
	v_fmac_f32_e32 v87, v88, v85
	v_fma_f32 v84, -v84, v87, v86
	v_div_fmas_f32 v84, v84, v85, v87
	v_div_fixup_f32 v84, v84, v7, 1.0
	v_pk_fma_f32 v[52:53], v[38:39], v[84:85], v[66:67] op_sel_hi:[1,0,1]
	v_pk_fma_f32 v[66:67], v[36:37], v[84:85], v[82:83] op_sel_hi:[1,0,1]
	v_pk_mul_f32 v[36:37], v[70:71], v[40:41]
	v_pk_mul_f32 v[38:39], v[54:55], v[42:43]
	v_pk_fma_f32 v[42:43], v[36:37], v[84:85], v[80:81] op_sel_hi:[1,0,1]
	v_pk_mul_f32 v[36:37], v[72:73], v[44:45]
	v_pk_fma_f32 v[40:41], v[38:39], v[84:85], v[64:65] op_sel_hi:[1,0,1]
; __device__ __forceinline__ unsigned pk2(float lo, float hi) { f32x2 v = {lo, hi}; bf16x2_t b = __builtin_convertvector(v, bf16x2_t); return __builtin_bit_cast(unsigned, b); }
; template <int NEXT, int SRC> __device__ __forceinline__ void norm_rows(const Args& a, const bf16* Fin, float coef, int i_post, int i_pre, int first, int NGW, int end, int lane) {
;     ...
;             for (int j = 0; j < 4; ++j) { const f32x4 g = ((const f32x4*)post)[lane + 64 * j]; x[q][j] = x[q][j] + f[q][j] * g * rstd; s2 += (x[q][j].x * x[q][j].x + x[q][j].y * x[q][j].y) + (x[q][j].z * x[q][j].z + x[q][j].w * x[q][j].w); }
;             if constexpr (NEXT == 0) {
; #pragma unroll
;                 for (int j = 0; j < 4; ++j) ((f32x4*)((float*)a.in[I_OUT + z] + O_Y + (size_t)m * DM))[lane + 64 * j] = x[q][j];
;             } else {
;                 if constexpr (NEXT == 1) {
; #pragma unroll
;                     for (int j = 0; j < 4; ++j) { u32x2 o; o.x = pk2(x[q][j].x, x[q][j].y); o.y = pk2(x[q][j].z, x[q][j].w); ((u32x2*)(XR + (size_t)m * DM))[lane + 64 * j] = o; }
;                 }
;                 float r2 = 1.f;
;                 if constexpr (NEXT == 1) r2 = 1.f / sqrtf(wave_sum(s2) * (1.f / DM) + EPS);
; #pragma unroll
;                 for (int j = 0; j < 4; ++j) {
;                     f32x4 g = {1.f, 1.f, 1.f, 1.f};
;                     if constexpr (NEXT == 1) g = ((const f32x4*)pre)[lane + 64 * j];
;                     u32x2 o; o.x = pk2(x[q][j].x * r2 * g.x, x[q][j].y * r2 * g.y); o.y = pk2(x[q][j].z * r2 * g.z, x[q][j].w * r2 * g.w);
;                     ((u32x2*)(XN + (size_t)m * DM))[lane + 64 * j] = o;
;                 }
	v_pk_mul_f32 v[38:39], v[56:57], v[46:47]
	v_pk_fma_f32 v[46:47], v[36:37], v[84:85], v[78:79] op_sel_hi:[1,0,1]
	v_pk_mul_f32 v[36:37], v[74:75], v[48:49]
	v_pk_fma_f32 v[44:45], v[38:39], v[84:85], v[62:63] op_sel_hi:[1,0,1]
	v_pk_mul_f32 v[38:39], v[58:59], v[50:51]
	v_pk_fma_f32 v[50:51], v[36:37], v[84:85], v[76:77] op_sel_hi:[1,0,1]
	v_cvt_pk_bf16_f32 v36, v66, v67
	v_cvt_pk_bf16_f32 v37, v52, v53
	global_store_dwordx2 v[32:33], v[36:37], off
	v_cvt_pk_bf16_f32 v36, v42, v43
	v_cvt_pk_bf16_f32 v37, v40, v41
	v_pk_fma_f32 v[48:49], v[38:39], v[84:85], v[60:61] op_sel_hi:[1,0,1]
	global_store_dwordx2 v[32:33], v[36:37], off offset:512
	v_cvt_pk_bf16_f32 v36, v46, v47
	v_cvt_pk_bf16_f32 v37, v44, v45
	global_store_dwordx2 v[32:33], v[36:37], off offset:1024
	v_cvt_pk_bf16_f32 v36, v50, v51
	v_cvt_pk_bf16_f32 v37, v48, v49
	global_store_dwordx2 v[32:33], v[36:37], off offset:1536
	s_nop 1
	v_mov_b64_e32 v[36:37], v[100:101]
	v_mov_b64_e32 v[38:39], v[102:103]
	v_mul_f32_e32 v33, v43, v43
	v_mul_f32_e32 v54, v41, v41
	v_fmac_f32_e32 v33, v42, v42
	v_fmac_f32_e32 v54, v40, v40
	v_mul_f32_e32 v7, v67, v67
	v_mul_f32_e32 v32, v53, v53
	v_add_f32_e32 v33, v33, v54
	v_mul_f32_e32 v54, v47, v47
	v_mul_f32_e32 v55, v45, v45
	v_fmac_f32_e32 v32, v52, v52
	v_fmac_f32_e32 v54, v46, v46
	v_fmac_f32_e32 v55, v44, v44
	v_fmac_f32_e32 v7, v66, v66
	v_add_f32_e32 v54, v54, v55
	v_mul_f32_e32 v55, v51, v51
	v_mul_f32_e32 v56, v49, v49
	v_add_f32_e32 v7, v7, v32
	v_fmac_f32_e32 v55, v50, v50
	v_fmac_f32_e32 v56, v48, v48
	v_add_f32_e32 v7, v7, v33
	v_add_f32_e32 v55, v55, v56
	v_add_f32_e32 v7, v54, v7
	v_add_f32_e32 v7, v55, v7
	s_nop 1
	v_add_f32_dpp v7, v7, v7 quad_perm:[1,0,3,2] row_mask:0xf bank_mask:0xf bound_ctrl:1
	s_nop 1
	v_add_f32_dpp v7, v7, v7 quad_perm:[2,3,0,1] row_mask:0xf bank_mask:0xf bound_ctrl:1
	s_nop 1
	v_add_f32_dpp v7, v7, v7 row_half_mirror row_mask:0xf bank_mask:0xf bound_ctrl:1
	s_nop 1
	v_add_f32_dpp v7, v7, v7 row_mirror row_mask:0xf bank_mask:0xf bound_ctrl:1
	v_mov_b32_e32 v32, v7
	s_nop 1
	v_permlane16_swap_b32_e32 v7, v32
	v_add_f32_e32 v7, v7, v32
	v_mov_b32_e32 v32, v7
	s_nop 1
	v_permlane32_swap_b32_e32 v7, v32
	v_add_f32_e32 v7, v7, v32
	v_fmamk_f32 v7, v7, 0x3a800000, v34
	v_mul_f32_e32 v32, 0x4f800000, v7
	v_cmp_gt_f32_e32 vcc, s24, v7
	s_nop 1
	v_cndmask_b32_e32 v7, v7, v32, vcc
	v_sqrt_f32_e32 v32, v7
	s_nop 0
	v_add_u32_e32 v33, -1, v32
	v_fma_f32 v54, -v33, v32, v7
	v_cmp_ge_f32_e64 s[6:7], 0, v54
	v_add_u32_e32 v54, 1, v32
	s_nop 0
	v_cndmask_b32_e64 v33, v32, v33, s[6:7]
	v_fma_f32 v32, -v54, v32, v7
	v_cmp_lt_f32_e64 s[6:7], 0, v32
	s_nop 1
	v_cndmask_b32_e64 v32, v33, v54, s[6:7]
	v_mul_f32_e32 v33, 0x37800000, v32
	v_cndmask_b32_e32 v32, v32, v33, vcc
	v_cmp_class_f32_e32 vcc, v7, v35
	s_nop 1
	v_cndmask_b32_e32 v7, v32, v7, vcc
	v_div_scale_f32 v32, s[6:7], v7, v7, 1.0
	v_rcp_f32_e32 v33, v32
	s_nop 0
	v_fma_f32 v54, -v32, v33, 1.0
	v_fmac_f32_e32 v33, v54, v33
	v_div_scale_f32 v54, vcc, 1.0, v7, 1.0
	v_mul_f32_e32 v55, v54, v33
	v_fma_f32 v56, -v32, v55, v54
	v_fmac_f32_e32 v55, v56, v33
	v_fma_f32 v32, -v32, v55, v54
	v_div_fmas_f32 v32, v32, v33, v55
	v_div_fixup_f32 v32, v32, v7, 1.0
	v_pk_mul_f32 v[54:55], v[66:67], v[32:33] op_sel_hi:[1,0]
	v_pk_mul_f32 v[52:53], v[52:53], v[32:33] op_sel_hi:[1,0]
	s_waitcnt vmcnt(4)
	v_pk_mul_f32 v[36:37], v[36:37], v[54:55]
	v_pk_mul_f32 v[38:39], v[38:39], v[52:53]
	v_add_co_u32_e32 v26, vcc, s25, v26
	v_cvt_pk_bf16_f32 v36, v36, v37
	v_cvt_pk_bf16_f32 v37, v38, v39
	v_addc_co_u32_e32 v27, vcc, 0, v27, vcc
	global_store_dwordx2 v[26:27], v[36:37], off
	s_nop 1
	v_mov_b64_e32 v[36:37], v[104:105]
	v_mov_b64_e32 v[38:39], v[106:107]
	v_pk_mul_f32 v[42:43], v[42:43], v[32:33] op_sel_hi:[1,0]
	v_pk_mul_f32 v[40:41], v[40:41], v[32:33] op_sel_hi:[1,0]
	v_pk_mul_f32 v[36:37], v[36:37], v[42:43]
	v_pk_mul_f32 v[38:39], v[38:39], v[40:41]
	v_cvt_pk_bf16_f32 v36, v36, v37
	v_cvt_pk_bf16_f32 v37, v38, v39
	global_store_dwordx2 v[26:27], v[36:37], off offset:512
	s_nop 1
	v_mov_b64_e32 v[36:37], v[108:109]
	v_mov_b64_e32 v[38:39], v[110:111]
	v_pk_mul_f32 v[40:41], v[46:47], v[32:33] op_sel_hi:[1,0]
	v_pk_mul_f32 v[42:43], v[44:45], v[32:33] op_sel_hi:[1,0]
	v_pk_mul_f32 v[36:37], v[36:37], v[40:41]
	v_pk_mul_f32 v[38:39], v[38:39], v[42:43]
	v_cvt_pk_bf16_f32 v36, v36, v37
	v_cvt_pk_bf16_f32 v37, v38, v39
	global_store_dwordx2 v[26:27], v[36:37], off offset:1024
	s_nop 1
	v_mov_b64_e32 v[36:37], v[112:113]
	v_mov_b64_e32 v[38:39], v[114:115]
	v_pk_mul_f32 v[40:41], v[50:51], v[32:33] op_sel_hi:[1,0]
	v_pk_mul_f32 v[32:33], v[48:49], v[32:33] op_sel_hi:[1,0]
	v_pk_mul_f32 v[36:37], v[36:37], v[40:41]
	v_pk_mul_f32 v[32:33], v[38:39], v[32:33]
	v_cvt_pk_bf16_f32 v36, v36, v37
	v_cvt_pk_bf16_f32 v37, v32, v33
	global_store_dwordx2 v[26:27], v[36:37], off offset:1536
	s_cbranch_scc1 .LBB0_1720
; __device__ __forceinline__ float bflo(unsigned w) { return __uint_as_float(w << 16); }
; __device__ __forceinline__ float bfhi(unsigned w) { return __uint_as_float(w & 0xffff0000u); }
; template <int NEXT, int SRC> __device__ __forceinline__ void norm_rows(const Args& a, const bf16* Fin, float coef, int i_post, int i_pre, int first, int NGW, int end, int lane) {
;     ...
;         for (int q = 0; q < 2; ++q) { const int m = m0 + q * NGW; const bool ok = m < end; const int mm = ok ? m : m0;
;             const float* xr = SRC == 0 ? xrow_ptr(a, mm, z) : nullptr;
;             const bf16* xb = (SRC == 1 ? XR : XN) + (size_t)mm * DM;
; #pragma unroll
;             for (int j = 0; j < 4; ++j) {
;                 const u32x2 w = ((const u32x2*)(Fin + (size_t)mm * DM))[lane + 64 * j];
;                 f[q][j] = (f32x4){bflo(w.x), bfhi(w.x), bflo(w.y), bfhi(w.y)};
;                 if constexpr (SRC == 0) x[q][j] = ((const f32x4*)xr)[lane + 64 * j];
;                 else { const u32x2 xw = ((const u32x2*)xb)[lane + 64 * j]; x[q][j] = (f32x4){bflo(xw.x), bfhi(xw.x), bflo(xw.y), bfhi(xw.y)}; }
;                 s[q] += (f[q][j].x * f[q][j].x + f[q][j].y * f[q][j].y) + (f[q][j].z * f[q][j].z + f[q][j].w * f[q][j].w);
;             } }
; #pragma unroll
;         for (int q = 0; q < 2; ++q) { const int m = m0 + q * NGW; if (m >= end) break;
;             const float rstd = coef / sqrtf(wave_sum(s[q]) * (1.f / DM) + EPS);
;             float s2 = 0.f;
; #pragma unroll
;             for (int j = 0; j < 4; ++j) { const f32x4 g = ((const f32x4*)post)[lane + 64 * j]; x[q][j] = x[q][j] + f[q][j] * g * rstd; s2 += (x[q][j].x * x[q][j].x + x[q][j].y * x[q][j].y) + (x[q][j].z * x[q][j].z + x[q][j].w * x[q][j].w); }
	v_and_b32_e32 v45, 0xffff0000, v30
	v_and_b32_e32 v47, 0xffff0000, v31
	v_lshlrev_b32_e32 v44, 16, v30
	v_mul_f32_e32 v7, v45, v45
	v_lshlrev_b32_e32 v46, 16, v31
	v_mul_f32_e32 v26, v47, v47
	v_fmac_f32_e32 v7, v44, v44
	v_fmac_f32_e32 v26, v46, v46
	v_and_b32_e32 v49, 0xffff0000, v28
	v_and_b32_e32 v51, 0xffff0000, v29
	v_add_f32_e32 v7, v7, v26
	v_lshlrev_b32_e32 v48, 16, v28
	v_mul_f32_e32 v26, v49, v49
	v_lshlrev_b32_e32 v50, 16, v29
	v_mul_f32_e32 v27, v51, v51
	v_fmac_f32_e32 v26, v48, v48
	v_fmac_f32_e32 v27, v50, v50
	v_add_f32_e32 v26, v26, v27
	v_lshlrev_b32_e32 v52, 16, v24
	v_and_b32_e32 v53, 0xffff0000, v24
	v_lshlrev_b32_e32 v24, 16, v25
	v_and_b32_e32 v25, 0xffff0000, v25
	v_add_f32_e32 v7, v7, v26
	v_mul_f32_e32 v36, v53, v53
	global_load_dwordx4 v[26:29], v[10:11], off
	global_load_dwordx4 v[30:33], v[10:11], off offset:1024
	v_mul_f32_e32 v37, v25, v25
	v_fmac_f32_e32 v36, v52, v52
	v_fmac_f32_e32 v37, v24, v24
	v_add_f32_e32 v40, v36, v37
	global_load_dwordx4 v[36:39], v[10:11], off offset:2048
	v_add_f32_e32 v7, v7, v40
	global_load_dwordx4 v[40:43], v[10:11], off offset:3072
	v_lshlrev_b32_e32 v54, 16, v22
	v_and_b32_e32 v55, 0xffff0000, v22
	v_lshlrev_b32_e32 v22, 16, v23
	v_and_b32_e32 v23, 0xffff0000, v23
	v_mul_f32_e32 v56, v55, v55
	v_mul_f32_e32 v57, v23, v23
	v_fmac_f32_e32 v56, v54, v54
	v_fmac_f32_e32 v57, v22, v22
	v_add_f32_e32 v56, v56, v57
	v_add_f32_e32 v7, v7, v56
	v_lshlrev_b32_e32 v60, 16, v16
	v_and_b32_e32 v61, 0xffff0000, v16
	v_add_f32_dpp v7, v7, v7 quad_perm:[1,0,3,2] row_mask:0xf bank_mask:0xf bound_ctrl:1
	v_lshlrev_b32_e32 v62, 16, v14
	v_lshlrev_b32_e32 v58, 16, v18
	v_add_f32_dpp v7, v7, v7 quad_perm:[2,3,0,1] row_mask:0xf bank_mask:0xf bound_ctrl:1
	v_and_b32_e32 v59, 0xffff0000, v18
	v_lshlrev_b32_e32 v18, 16, v19
	v_add_f32_dpp v7, v7, v7 row_half_mirror row_mask:0xf bank_mask:0xf bound_ctrl:1
	v_and_b32_e32 v19, 0xffff0000, v19
	v_lshlrev_b32_e32 v56, 16, v20
	v_add_f32_dpp v7, v7, v7 row_mirror row_mask:0xf bank_mask:0xf bound_ctrl:1
	v_mov_b32_e32 v16, v7
	s_nop 1
	v_permlane16_swap_b32_e32 v7, v16
	v_add_f32_e32 v7, v7, v16
	v_mov_b32_e32 v16, v7
	s_nop 1
	v_permlane32_swap_b32_e32 v7, v16
	v_add_f32_e32 v7, v7, v16
	v_fmamk_f32 v7, v7, 0x3a800000, v34
	v_mul_f32_e32 v16, 0x4f800000, v7
	v_cmp_gt_f32_e32 vcc, s24, v7
	v_and_b32_e32 v57, 0xffff0000, v20
	v_lshlrev_b32_e32 v20, 16, v21
	v_cndmask_b32_e32 v7, v7, v16, vcc
	v_sqrt_f32_e32 v63, v7
	v_lshlrev_b32_e32 v16, 16, v17
	v_and_b32_e32 v17, 0xffff0000, v17
	v_and_b32_e32 v21, 0xffff0000, v21
	v_add_u32_e32 v64, -1, v63
	v_fma_f32 v65, -v64, v63, v7
	v_cmp_ge_f32_e64 s[6:7], 0, v65
	v_add_u32_e32 v65, 1, v63
	s_waitcnt vmcnt(3)
	v_pk_mul_f32 v[28:29], v[46:47], v[28:29]
	v_cndmask_b32_e64 v64, v63, v64, s[6:7]
	v_fma_f32 v63, -v65, v63, v7
	v_cmp_lt_f32_e64 s[6:7], 0, v63
	v_pk_mul_f32 v[26:27], v[44:45], v[26:27]
	s_nop 0
	v_cndmask_b32_e64 v63, v64, v65, s[6:7]
	v_mul_f32_e32 v64, 0x37800000, v63
	v_cndmask_b32_e32 v63, v63, v64, vcc
	v_cmp_class_f32_e32 vcc, v7, v35
	s_nop 1
	v_cndmask_b32_e32 v7, v63, v7, vcc
	v_div_scale_f32 v64, s[6:7], v7, v7, 1.0
	v_rcp_f32_e32 v65, v64
	v_and_b32_e32 v63, 0xffff0000, v14
	v_lshlrev_b32_e32 v14, 16, v15
	v_and_b32_e32 v15, 0xffff0000, v15
	v_fma_f32 v66, -v64, v65, 1.0
	v_fmac_f32_e32 v65, v66, v65
	v_div_scale_f32 v66, vcc, 1.0, v7, 1.0
	v_mul_f32_e32 v67, v66, v65
	v_fma_f32 v68, -v64, v67, v66
	v_fmac_f32_e32 v67, v68, v65
	v_fma_f32 v64, -v64, v67, v66
	v_div_fmas_f32 v64, v64, v65, v67
	v_div_fixup_f32 v64, v64, v7, 1.0
	v_pk_fma_f32 v[28:29], v[28:29], v[64:65], v[14:15] op_sel_hi:[1,0,1]
	s_waitcnt vmcnt(2)
	v_pk_mul_f32 v[14:15], v[48:49], v[30:31]
	v_pk_mul_f32 v[30:31], v[50:51], v[32:33]
	v_pk_fma_f32 v[32:33], v[14:15], v[64:65], v[60:61] op_sel_hi:[1,0,1]
	v_pk_fma_f32 v[30:31], v[30:31], v[64:65], v[16:17] op_sel_hi:[1,0,1]
	s_waitcnt vmcnt(1)
	v_pk_mul_f32 v[16:17], v[24:25], v[38:39]
	v_pk_mul_f32 v[14:15], v[52:53], v[36:37]
	v_pk_fma_f32 v[18:19], v[16:17], v[64:65], v[18:19] op_sel_hi:[1,0,1]
	s_waitcnt vmcnt(0)
; __device__ __forceinline__ unsigned pk2(float lo, float hi) { f32x2 v = {lo, hi}; bf16x2_t b = __builtin_convertvector(v, bf16x2_t); return __builtin_bit_cast(unsigned, b); }
; template <int NEXT, int SRC> __device__ __forceinline__ void norm_rows(const Args& a, const bf16* Fin, float coef, int i_post, int i_pre, int first, int NGW, int end, int lane) {
;     ...
;             for (int j = 0; j < 4; ++j) { const f32x4 g = ((const f32x4*)post)[lane + 64 * j]; x[q][j] = x[q][j] + f[q][j] * g * rstd; s2 += (x[q][j].x * x[q][j].x + x[q][j].y * x[q][j].y) + (x[q][j].z * x[q][j].z + x[q][j].w * x[q][j].w); }
;             if constexpr (NEXT == 0) {
; #pragma unroll
;                 for (int j = 0; j < 4; ++j) ((f32x4*)((float*)a.in[I_OUT + z] + O_Y + (size_t)m * DM))[lane + 64 * j] = x[q][j];
;             } else {
;                 if constexpr (NEXT == 1) {
; #pragma unroll
;                     for (int j = 0; j < 4; ++j) { u32x2 o; o.x = pk2(x[q][j].x, x[q][j].y); o.y = pk2(x[q][j].z, x[q][j].w); ((u32x2*)(XR + (size_t)m * DM))[lane + 64 * j] = o; }
;                 }
;                 float r2 = 1.f;
;                 if constexpr (NEXT == 1) r2 = 1.f / sqrtf(wave_sum(s2) * (1.f / DM) + EPS);
; #pragma unroll
;                 for (int j = 0; j < 4; ++j) {
;                     f32x4 g = {1.f, 1.f, 1.f, 1.f};
;                     if constexpr (NEXT == 1) g = ((const f32x4*)pre)[lane + 64 * j];
;                     u32x2 o; o.x = pk2(x[q][j].x * r2 * g.x, x[q][j].y * r2 * g.y); o.y = pk2(x[q][j].z * r2 * g.z, x[q][j].w * r2 * g.w);
;                     ((u32x2*)(XN + (size_t)m * DM))[lane + 64 * j] = o;
;                 }
	v_pk_mul_f32 v[16:17], v[22:23], v[42:43]
	v_lshl_add_u64 v[36:37], s[16:17], 0, v[2:3]
	v_pk_fma_f32 v[26:27], v[26:27], v[64:65], v[62:63] op_sel_hi:[1,0,1]
	v_pk_fma_f32 v[24:25], v[14:15], v[64:65], v[58:59] op_sel_hi:[1,0,1]
	v_pk_mul_f32 v[14:15], v[54:55], v[40:41]
	v_pk_fma_f32 v[20:21], v[16:17], v[64:65], v[20:21] op_sel_hi:[1,0,1]
	v_add_co_u32_e32 v16, vcc, s23, v36
	v_pk_fma_f32 v[22:23], v[14:15], v[64:65], v[56:57] op_sel_hi:[1,0,1]
	v_cvt_pk_bf16_f32 v14, v26, v27
	v_cvt_pk_bf16_f32 v15, v28, v29
	v_addc_co_u32_e32 v17, vcc, 0, v37, vcc
	global_store_dwordx2 v[16:17], v[14:15], off
	v_cvt_pk_bf16_f32 v14, v32, v33
	v_cvt_pk_bf16_f32 v15, v30, v31
	global_store_dwordx2 v[16:17], v[14:15], off offset:512
	v_cvt_pk_bf16_f32 v14, v24, v25
	v_cvt_pk_bf16_f32 v15, v18, v19
	global_store_dwordx2 v[16:17], v[14:15], off offset:1024
	v_cvt_pk_bf16_f32 v14, v22, v23
	v_cvt_pk_bf16_f32 v15, v20, v21
	global_store_dwordx2 v[16:17], v[14:15], off offset:1536
	s_nop 1
	v_mov_b64_e32 v[14:15], v[100:101]
	v_mov_b64_e32 v[16:17], v[102:103]
	v_mul_f32_e32 v39, v33, v33
	v_mul_f32_e32 v40, v31, v31
	v_fmac_f32_e32 v39, v32, v32
	v_fmac_f32_e32 v40, v30, v30
	v_mul_f32_e32 v7, v27, v27
	v_mul_f32_e32 v38, v29, v29
	v_add_f32_e32 v39, v39, v40
	v_mul_f32_e32 v40, v25, v25
	v_mul_f32_e32 v41, v19, v19
	v_fmac_f32_e32 v38, v28, v28
	v_fmac_f32_e32 v40, v24, v24
	v_fmac_f32_e32 v41, v18, v18
	v_fmac_f32_e32 v7, v26, v26
	v_add_f32_e32 v40, v40, v41
	v_mul_f32_e32 v41, v23, v23
	v_mul_f32_e32 v42, v21, v21
	v_add_f32_e32 v7, v7, v38
	v_fmac_f32_e32 v41, v22, v22
	v_fmac_f32_e32 v42, v20, v20
	v_add_f32_e32 v7, v7, v39
	v_add_f32_e32 v41, v41, v42
	v_add_f32_e32 v7, v40, v7
	v_add_f32_e32 v7, v41, v7
	s_nop 1
	v_add_f32_dpp v7, v7, v7 quad_perm:[1,0,3,2] row_mask:0xf bank_mask:0xf bound_ctrl:1
	s_nop 1
	v_add_f32_dpp v7, v7, v7 quad_perm:[2,3,0,1] row_mask:0xf bank_mask:0xf bound_ctrl:1
	s_nop 1
	v_add_f32_dpp v7, v7, v7 row_half_mirror row_mask:0xf bank_mask:0xf bound_ctrl:1
	s_nop 1
	v_add_f32_dpp v7, v7, v7 row_mirror row_mask:0xf bank_mask:0xf bound_ctrl:1
	v_mov_b32_e32 v38, v7
	s_nop 1
	v_permlane16_swap_b32_e32 v7, v38
	v_add_f32_e32 v7, v7, v38
	v_mov_b32_e32 v38, v7
	s_nop 1
	v_permlane32_swap_b32_e32 v7, v38
	v_add_f32_e32 v7, v7, v38
	v_fmamk_f32 v7, v7, 0x3a800000, v34
	v_mul_f32_e32 v38, 0x4f800000, v7
	v_cmp_gt_f32_e32 vcc, s24, v7
	s_nop 1
	v_cndmask_b32_e32 v7, v7, v38, vcc
	v_sqrt_f32_e32 v38, v7
	s_nop 0
	v_add_u32_e32 v39, -1, v38
	v_fma_f32 v40, -v39, v38, v7
	v_cmp_ge_f32_e64 s[6:7], 0, v40
	v_add_u32_e32 v40, 1, v38
	s_nop 0
	v_cndmask_b32_e64 v39, v38, v39, s[6:7]
	v_fma_f32 v38, -v40, v38, v7
	v_cmp_lt_f32_e64 s[6:7], 0, v38
	s_nop 1
	v_cndmask_b32_e64 v38, v39, v40, s[6:7]
	v_mul_f32_e32 v39, 0x37800000, v38
	v_cndmask_b32_e32 v38, v38, v39, vcc
	v_cmp_class_f32_e32 vcc, v7, v35
	s_nop 1
	v_cndmask_b32_e32 v7, v38, v7, vcc
	v_div_scale_f32 v38, s[6:7], v7, v7, 1.0
	v_rcp_f32_e32 v39, v38
	s_nop 0
	v_fma_f32 v40, -v38, v39, 1.0
	v_fmac_f32_e32 v39, v40, v39
	v_div_scale_f32 v40, vcc, 1.0, v7, 1.0
	v_mul_f32_e32 v41, v40, v39
	v_fma_f32 v42, -v38, v41, v40
	v_fmac_f32_e32 v41, v42, v39
	v_fma_f32 v38, -v38, v41, v40
	v_div_fmas_f32 v38, v38, v39, v41
	v_div_fixup_f32 v38, v38, v7, 1.0
	v_pk_mul_f32 v[26:27], v[26:27], v[38:39] op_sel_hi:[1,0]
	v_pk_mul_f32 v[30:31], v[30:31], v[38:39] op_sel_hi:[1,0]
	v_pk_mul_f32 v[14:15], v[14:15], v[26:27]
	v_pk_mul_f32 v[26:27], v[28:29], v[38:39] op_sel_hi:[1,0]
	v_cvt_pk_bf16_f32 v14, v14, v15
	v_pk_mul_f32 v[16:17], v[16:17], v[26:27]
	v_add_co_u32_e32 v26, vcc, s25, v36
	v_cvt_pk_bf16_f32 v15, v16, v17
	s_nop 0
	v_addc_co_u32_e32 v27, vcc, 0, v37, vcc
	global_store_dwordx2 v[26:27], v[14:15], off
	s_nop 1
	v_mov_b64_e32 v[14:15], v[104:105]
	v_mov_b64_e32 v[16:17], v[106:107]
	v_pk_mul_f32 v[28:29], v[32:33], v[38:39] op_sel_hi:[1,0]
	v_pk_mul_f32 v[24:25], v[24:25], v[38:39] op_sel_hi:[1,0]
	v_pk_mul_f32 v[18:19], v[18:19], v[38:39] op_sel_hi:[1,0]
	v_pk_mul_f32 v[20:21], v[20:21], v[38:39] op_sel_hi:[1,0]
	v_pk_mul_f32 v[14:15], v[14:15], v[28:29]
	v_pk_mul_f32 v[16:17], v[16:17], v[30:31]
	v_cvt_pk_bf16_f32 v14, v14, v15
	v_cvt_pk_bf16_f32 v15, v16, v17
	global_store_dwordx2 v[26:27], v[14:15], off offset:512
	s_nop 1
	v_mov_b64_e32 v[14:15], v[108:109]
	v_mov_b64_e32 v[16:17], v[110:111]
	v_pk_mul_f32 v[14:15], v[14:15], v[24:25]
	v_pk_mul_f32 v[16:17], v[16:17], v[18:19]
	v_cvt_pk_bf16_f32 v14, v14, v15
	v_cvt_pk_bf16_f32 v15, v16, v17
	global_store_dwordx2 v[26:27], v[14:15], off offset:1024
	s_nop 1
	v_mov_b64_e32 v[14:15], v[112:113]
	v_mov_b64_e32 v[16:17], v[114:115]
	v_pk_mul_f32 v[18:19], v[22:23], v[38:39] op_sel_hi:[1,0]
	v_pk_mul_f32 v[16:17], v[16:17], v[20:21]
	v_pk_mul_f32 v[14:15], v[14:15], v[18:19]
	s_nop 0
	v_cvt_pk_bf16_f32 v14, v14, v15
	v_cvt_pk_bf16_f32 v15, v16, v17
	global_store_dwordx2 v[26:27], v[14:15], off offset:1536
	s_branch .LBB0_1720
